# first XCD barrier: the 16 per-XCD census loads issued together instead of one round trip each
# baseline (speedup 1.0000x reference)
.Lgs0_221:
	v_readlane_b32 s2, v243, 8
	v_readlane_b32 s3, v243, 9
	v_readlane_b32 s5, v243, 5
	s_mov_b64 s[22:23], -1
	s_nop 2
	global_load_dword v0, v1, s[2:3] sc1
	v_readlane_b32 s2, v243, 10
	v_readlane_b32 s3, v243, 11
	s_waitcnt lgkmcnt(0)
	s_nop 3
	global_load_dword v2, v1, s[2:3] sc1
	v_readlane_b32 s2, v243, 12
	v_readlane_b32 s3, v243, 13
	s_nop 0
	s_nop 0
	s_nop 2
	global_load_dword v3, v1, s[2:3] sc1
	v_readlane_b32 s2, v243, 14
	v_readlane_b32 s3, v243, 15
	s_nop 0
	s_nop 0
	s_nop 2
	global_load_dword v4, v1, s[2:3] sc1
	v_readlane_b32 s2, v243, 16
	v_readlane_b32 s3, v243, 17
	s_nop 0
	s_nop 0
	s_nop 2
	global_load_dword v5, v1, s[2:3] sc1
	v_readlane_b32 s2, v243, 18
	v_readlane_b32 s3, v243, 19
	s_nop 0
	s_nop 0
	s_nop 2
	global_load_dword v6, v1, s[2:3] sc1
	v_readlane_b32 s2, v243, 20
	v_readlane_b32 s3, v243, 21
	s_nop 0
	s_nop 0
	s_nop 2
	global_load_dword v7, v1, s[2:3] sc1
	v_readlane_b32 s2, v243, 22
	v_readlane_b32 s3, v243, 23
	s_nop 0
	s_nop 0
	s_nop 2
	global_load_dword v8, v1, s[2:3] sc1
	v_readlane_b32 s2, v243, 24
	v_readlane_b32 s3, v243, 25
	s_nop 0
	s_nop 0
	s_nop 2
	global_load_dword v9, v1, s[2:3] sc1
	v_readlane_b32 s2, v243, 26
	v_readlane_b32 s3, v243, 27
	s_nop 0
	s_nop 0
	s_nop 2
	global_load_dword v10, v1, s[2:3] sc1
	v_readlane_b32 s2, v243, 28
	v_readlane_b32 s3, v243, 29
	s_nop 0
	s_nop 0
	s_nop 2
	global_load_dword v11, v1, s[2:3] sc1
	v_readlane_b32 s2, v243, 30
	v_readlane_b32 s3, v243, 31
	s_nop 0
	s_nop 0
	s_nop 2
	global_load_dword v12, v1, s[2:3] sc1
	v_readlane_b32 s2, v243, 32
	v_readlane_b32 s3, v243, 33
	s_nop 0
	s_nop 0
	s_nop 2
	global_load_dword v13, v1, s[2:3] sc1
	v_readlane_b32 s2, v243, 34
	v_readlane_b32 s3, v243, 35
	s_nop 0
	s_nop 0
	s_nop 2
	global_load_dword v14, v1, s[2:3] sc1
	v_readlane_b32 s2, v243, 36
	v_readlane_b32 s3, v243, 37
	s_nop 0
	s_nop 0
	s_nop 2
	global_load_dword v15, v1, s[2:3] sc1
	v_readlane_b32 s2, v243, 38
	v_readlane_b32 s3, v243, 39
	s_nop 0
	s_nop 0
	s_nop 2
	global_load_dword v16, v1, s[2:3] sc1
	s_mov_b64 s[2:3], -1
	s_nop 0
	s_nop 0
	s_waitcnt vmcnt(0)
	v_add_u32_e32 v17, v2, v0
	v_add_u32_e32 v17, v17, v3
	v_add_u32_e32 v17, v17, v4
	v_add_u32_e32 v17, v17, v5
	v_add_u32_e32 v17, v17, v6
	v_add_u32_e32 v17, v17, v7
	v_add_u32_e32 v17, v17, v8
	v_add_u32_e32 v17, v17, v9
	v_add_u32_e32 v17, v17, v10
	v_add_u32_e32 v17, v17, v11
	v_add_u32_e32 v17, v17, v12
	v_add_u32_e32 v17, v17, v13
	v_add_u32_e32 v17, v17, v14
	v_add_u32_e32 v17, v17, v15
	v_add_u32_e32 v17, v17, v16
	v_cmp_eq_u32_e32 vcc, s5, v17
	s_cbranch_vccnz .Lgs0_220
	s_and_b32 s2, s4, 0xff
	s_cmp_eq_u32 s2, 0
	s_mov_b64 s[2:3], -1
	s_mov_b64 s[34:35], -1
	s_sleep 1
	s_cbranch_scc1 .Lgs0_225
	s_and_b64 vcc, exec, s[34:35]
	s_cbranch_vccz .Lgs0_220
